# attention: next step's K/V tile loads issued at the tail of the MFMA segment (slack before its barrier) instead of the softmax head
# speedup vs baseline: 1.0036x; 1.0036x over previous
; #define ATT_BAR() do { asm volatile("s_waitcnt lgkmcnt(0)" ::: "memory"); __builtin_amdgcn_s_barrier(); asm volatile("" ::: "memory"); } while (0)
; template <int DK, int DV>
; __device__ __forceinline__ void attn_unit(LAS unsigned char* lds, const bf16* Qp, int ldq, const bf16* Kp, int ldk, const bf16* VTp, bf16* Op, int ldo, int qb) {
;     ...
;     ATT_LOAD(0, kra, vra); ATT_LOAD(1, krb, vrb);
;     ATT_STORE(0, kra, vra); ATT_STORE(BUF, krb, vrb);
;     ATT_LOAD(2, krb, vrb);
;     __syncthreads();
;     float mrun = 0.f, lrun = 0.f;
;     f32x16 o[NDB];
; #pragma unroll
;     for (int db = 0; db < NDB; ++db)
; #pragma unroll
;         for (int r = 0; r < 16; ++r) o[db][r] = 0.f;
;     f32x16 s0, s1;
;     const f32x16 zacc = {0.f, 0.f, 0.f, 0.f, 0.f, 0.f, 0.f, 0.f, 0.f, 0.f, 0.f, 0.f, 0.f, 0.f, 0.f, 0.f};
;     f32x16 negm = zacc;
;     constexpr float ATT_THR = 8.f;
;     ATT_QK(0, zacc);
;     if (grpB) ATT_BAR();
;     int bcur = 0, bnext = BUF, bfree = 2 * BUF;
.LBB0_1036:
	ds_read_b128 v[196:199], v141
	ds_read_b128 v[200:203], v141 offset:1024
	ds_read_b128 v[204:207], v141 offset:2048
	ds_read_b128 v[208:211], v141 offset:3072
	ds_read_b128 v[212:215], v141 offset:4096
	ds_read_b128 v[216:219], v141 offset:5120
	v_or_b32_e32 v159, s46, v6
	v_mul_u32_u24_e32 v6, 0x90, v6
	v_lshlrev_b32_e32 v158, 2, v7
	v_lshl_add_u64 v[144:145], v[2:3], 1, s[4:5]
	v_lshl_add_u64 v[146:147], v[4:5], 1, s[4:5]
	v_mad_i64_i32 v[186:187], vcc, v150, s3, v[144:145]
	v_mad_i64_i32 v[188:189], vcc, v151, s3, v[146:147]
	v_add3_u32 v160, 0, v6, v0
	v_mov_b32_e32 v2, v1
	v_mov_b32_e32 v3, v1
	v_mov_b32_e32 v4, v1
	v_mov_b32_e32 v5, v1
	v_mov_b32_e32 v6, v1
	v_mov_b32_e32 v7, v1
	v_mov_b32_e32 v8, v1
	v_mov_b32_e32 v9, v1
	v_mov_b32_e32 v10, v1
	v_mov_b32_e32 v11, v1
	v_mov_b32_e32 v12, v1
	v_mov_b32_e32 v13, v1
	v_mov_b32_e32 v14, v1
	v_mov_b32_e32 v15, v1
	v_mov_b32_e32 v16, v1
	v_mov_b32_e32 v17, v1
	v_mov_b32_e32 v18, v1
	v_mov_b32_e32 v19, v1
	v_mov_b32_e32 v20, v1
	v_mov_b32_e32 v21, v1
	v_mov_b32_e32 v22, v1
	v_mov_b32_e32 v23, v1
	v_mov_b32_e32 v24, v1
	v_mov_b32_e32 v25, v1
	v_mov_b32_e32 v26, v1
	v_mov_b32_e32 v27, v1
	v_mov_b32_e32 v28, v1
	v_mov_b32_e32 v29, v1
	v_mov_b32_e32 v30, v1
	v_mov_b32_e32 v31, v1
	s_lshl_b32 s48, s0, 2
	v_mov_b32_e32 v0, v1
	v_mov_b64_e32 v[32:33], v[30:31]
	s_lshl_b32 s47, s1, 13
	v_ashrrev_i32_e32 v139, 31, v138
	s_add_i32 s49, s48, 4
	s_or_b32 s50, s48, 3
	s_or_b32 s51, s46, 31
	s_mov_b32 s54, 0
	s_sub_i32 s55, 0, s48
	s_sub_i32 s56, 0, s8
	v_subrev_u32_e32 v161, s8, v158
	v_mov_b32_e32 v66, v1
	v_mov_b32_e32 v67, v1
	v_mov_b32_e32 v68, v1
	v_mov_b32_e32 v69, v1
	v_mov_b32_e32 v70, v1
	v_mov_b32_e32 v71, v1
	v_mov_b32_e32 v72, v1
	v_mov_b32_e32 v73, v1
	v_mov_b32_e32 v74, v1
	v_mov_b32_e32 v75, v1
	v_mov_b32_e32 v76, v1
	v_mov_b32_e32 v77, v1
	v_mov_b32_e32 v78, v1
	v_mov_b32_e32 v79, v1
	v_mov_b32_e32 v80, v1
	v_mov_b32_e32 v81, v1
	s_mov_b32 s57, 0xb000
	s_movk_i32 s58, 0x5800
	v_mov_b32_e32 v162, 0
	v_mov_b32_e32 v163, 0
	s_mov_b32 s0, 0
	s_mov_b32 s59, 0
	v_mov_b64_e32 v[30:31], v[28:29]
	v_mov_b64_e32 v[28:29], v[26:27]
	v_mov_b64_e32 v[26:27], v[24:25]
	v_mov_b64_e32 v[24:25], v[22:23]
	v_mov_b64_e32 v[22:23], v[20:21]
	v_mov_b64_e32 v[20:21], v[18:19]
	v_mov_b64_e32 v[18:19], v[16:17]
	v_mov_b64_e32 v[16:17], v[14:15]
	v_mov_b64_e32 v[14:15], v[12:13]
	v_mov_b64_e32 v[12:13], v[10:11]
	v_mov_b64_e32 v[10:11], v[8:9]
	v_mov_b64_e32 v[8:9], v[6:7]
	v_mov_b64_e32 v[6:7], v[4:5]
	v_mov_b64_e32 v[4:5], v[2:3]
	v_mov_b64_e32 v[2:3], v[0:1]
	s_add_i32 s1, s59, 3
	s_cmp_lt_u32 s1, s49
	s_cselect_b32 s1, s1, s50
	s_lshl_b32 s8, s1, 6
	s_mul_i32 s4, s8, 0x600
	s_mov_b32 s5, 0
	v_lshl_add_u64 v[94:95], s[4:5], 0, v[186:187]
	v_lshl_add_u64 v[96:97], s[4:5], 0, v[188:189]
	v_lshl_add_u64 v[102:103], s[8:9], 1, v[142:143]
	global_load_dwordx4 v[98:101], v[94:95], off
	s_nop 0
	global_load_dwordx4 v[94:97], v[96:97], off
	global_load_dwordx4 v[102:105], v[102:103], off
.LBB0_1037:
	s_add_i32 s62, s55, s59
	s_cmp_lt_i32 s62, 0
	s_cselect_b64 s[18:19], -1, 0
	s_add_i32 s61, s56, s54
	s_cmp_le_i32 s61, s51
	s_cselect_b64 s[4:5], -1, 0
	s_or_b64 s[20:21], s[18:19], s[4:5]
	s_mov_b32 s60, s58
	s_not_b64 s[4:5], s[20:21]
	s_andn2_b64 vcc, exec, s[20:21]
	s_mov_b32 s58, s0
	v_add_u32_e32 v248, s58, v160
	ds_read_b128 v[164:167], v248 offset:13312
	ds_read_b128 v[168:171], v248 offset:17920
	ds_read_b128 v[172:175], v248 offset:13344
	ds_read_b128 v[176:179], v248 offset:17952
	ds_read_b128 v[180:183], v248 offset:13376
	ds_read_b128 v[220:223], v248 offset:17984
	ds_read_b128 v[224:227], v248 offset:13408
	ds_read_b128 v[232:235], v248 offset:18016
	s_cbranch_vccnz .LBB0_1049
	s_cmp_lt_i32 s62, 0
	s_cbranch_scc0 .Lmla_a_mask

.LBB0_1053:
	s_setprio 0
	s_add_i32 s0, s59, 4
	s_cmp_lt_u32 s59, s48
	s_cselect_b32 s0, s0, s50
	s_lshl_b32 s8, s0, 6
	s_mul_i32 s0, s8, 0x600
	s_mov_b32 s1, 0
	v_lshl_add_u64 v[82:83], s[0:1], 0, v[186:187]
	v_lshl_add_u64 v[84:85], s[0:1], 0, v[188:189]
	global_load_dwordx4 v[86:89], v[82:83], off
	global_load_dwordx4 v[90:93], v[84:85], off
	v_lshl_add_u64 v[82:83], s[8:9], 1, v[142:143]
	global_load_dwordx4 v[82:85], v[82:83], off
	s_waitcnt lgkmcnt(0)
	s_barrier
	v_add_u32_e32 v248, s60, v160
	ds_read_b128 v[164:167], v248 offset:13312
	ds_read_b128 v[168:171], v248 offset:17920
	ds_read_b128 v[172:175], v248 offset:13344
	ds_read_b128 v[176:179], v248 offset:17952
	ds_read_b128 v[180:183], v248 offset:13376
	ds_read_b128 v[220:223], v248 offset:17984
	ds_read_b128 v[224:227], v248 offset:13408
	ds_read_b128 v[232:235], v248 offset:18016
	s_add_i32 s62, s62, 1
	s_cmp_lt_i32 s62, 0
	s_cselect_b64 s[0:1], -1, 0
	s_add_i32 s4, s61, 64
	s_cmp_le_i32 s4, s51
	s_cselect_b64 s[4:5], -1, 0
	s_or_b64 s[0:1], s[0:1], s[4:5]
	s_not_b64 s[4:5], s[0:1]
	s_andn2_b64 vcc, exec, s[0:1]
	s_cbranch_vccnz .LBB0_1059
	s_cmp_lt_i32 s62, 0
	s_cbranch_scc0 .Lmla_b_mask

; template <int DK, int DV>
; __device__ __forceinline__ void attn_unit(LAS unsigned char* lds, const bf16* Qp, int ldq, const bf16* Kp, int ldk, const bf16* VTp, bf16* Op, int ldo, int qb) {
;     ...
;     for (int t = 0; t < NT; t += 2) {
;         ATT_STEP(t, kra, vra, krb, vrb);
;         ATT_STEP(t + 1, krb, vrb, kra, vra);
;     }
.LBB0_1063:
	s_setprio 0
	s_and_b64 vcc, exec, s[4:5]
	s_cbranch_vccnz .Lmla_b_nold
	s_add_i32 s1, s59, 3
	s_cmp_lt_u32 s1, s49
	s_cselect_b32 s1, s1, s50
	s_lshl_b32 s8, s1, 6
	s_mul_i32 s20, s8, 0x600
	s_mov_b32 s21, 0
	v_lshl_add_u64 v[94:95], s[20:21], 0, v[186:187]
	v_lshl_add_u64 v[96:97], s[20:21], 0, v[188:189]
	v_lshl_add_u64 v[102:103], s[8:9], 1, v[142:143]
	global_load_dwordx4 v[98:101], v[94:95], off
	s_nop 0
	global_load_dwordx4 v[94:97], v[96:97], off
	global_load_dwordx4 v[102:105], v[102:103], off
.Lmla_b_nold:
	s_waitcnt lgkmcnt(0)
	s_barrier
	s_addk_i32 s54, 0x80
	s_and_b64 vcc, exec, s[4:5]
	s_cbranch_vccnz .LBB0_1065
	s_mov_b32 s0, s57
	s_mov_b32 s57, s60
	s_branch .LBB0_1037

; #define ATT_BAR() do { asm volatile("s_waitcnt lgkmcnt(0)" ::: "memory"); __builtin_amdgcn_s_barrier(); asm volatile("" ::: "memory"); } while (0)
; template <int DK, int DV>
; __device__ __forceinline__ void attn_unit(LAS unsigned char* lds, const bf16* Qp, int ldq, const bf16* Kp, int ldk, const bf16* VTp, bf16* Op, int ldo, int qb) {
;     ...
;     ATT_LOAD(0, kra, vra); ATT_LOAD(1, krb, vrb);
;     ATT_STORE(0, kra, vra); ATT_STORE(BUF, krb, vrb);
;     ATT_LOAD(2, krb, vrb);
;     __syncthreads();
;     float mrun = 0.f, lrun = 0.f;
;     f32x16 o[NDB];
; #pragma unroll
;     for (int db = 0; db < NDB; ++db)
; #pragma unroll
;         for (int r = 0; r < 16; ++r) o[db][r] = 0.f;
;     f32x16 s0, s1;
;     const f32x16 zacc = {0.f, 0.f, 0.f, 0.f, 0.f, 0.f, 0.f, 0.f, 0.f, 0.f, 0.f, 0.f, 0.f, 0.f, 0.f, 0.f};
;     f32x16 negm = zacc;
;     constexpr float ATT_THR = 8.f;
;     ATT_QK(0, zacc);
;     if (grpB) ATT_BAR();
;     int bcur = 0, bnext = BUF, bfree = 2 * BUF;
.LBB0_1071:
	ds_read_b128 v[232:235], v189
	ds_read_b128 v[236:239], v189 offset:1024
	ds_read_b128 v[240:243], v189 offset:2048
	ds_read_b128 v[244:247], v189 offset:3072
	v_mov_b32_e32 v14, v1
	v_mov_b32_e32 v15, v1
	s_lshl_b32 s43, s1, 2
	v_lshl_add_u64 v[182:183], v[2:3], 1, s[4:5]
	v_or_b32_e32 v192, s35, v4
	v_lshlrev_b32_e32 v191, 2, v5
	v_mov_b32_e32 v0, v1
	v_mov_b32_e32 v2, v1
	v_mov_b32_e32 v3, v1
	v_mov_b32_e32 v4, v1
	v_mov_b32_e32 v5, v1
	v_mov_b32_e32 v6, v1
	v_mov_b32_e32 v7, v1
	v_mov_b32_e32 v8, v1
	v_mov_b32_e32 v9, v1
	v_mov_b32_e32 v10, v1
	v_mov_b32_e32 v11, v1
	v_mov_b32_e32 v12, v1
	v_mov_b32_e32 v13, v1
	v_mov_b64_e32 v[30:31], v[14:15]
	v_mov_b64_e32 v[46:47], v[14:15]
	v_mov_b64_e32 v[62:63], v[14:15]
	v_mov_b64_e32 v[78:79], v[14:15]
	v_mov_b64_e32 v[126:127], v[14:15]
	s_lshl_b32 s42, s0, 13
	s_add_i32 s44, s43, 4
	s_or_b32 s45, s43, 3
	s_or_b32 s46, s35, 31
	s_mov_b32 s47, 0
	s_sub_i32 s48, 0, s43
	s_sub_i32 s49, 0, s8
	v_subrev_u32_e32 v194, s8, v191
	s_mov_b32 s50, 0xd800
	s_movk_i32 s51, 0x6c00
	v_mov_b32_e32 v193, 0
	v_mov_b64_e32 v[28:29], v[12:13]
	v_mov_b64_e32 v[26:27], v[10:11]
	v_mov_b64_e32 v[24:25], v[8:9]
	v_mov_b64_e32 v[22:23], v[6:7]
	v_mov_b64_e32 v[20:21], v[4:5]
	v_mov_b64_e32 v[18:19], v[2:3]
	v_mov_b64_e32 v[16:17], v[0:1]
	v_mov_b64_e32 v[44:45], v[12:13]
	v_mov_b64_e32 v[42:43], v[10:11]
	v_mov_b64_e32 v[40:41], v[8:9]
	v_mov_b64_e32 v[38:39], v[6:7]
	v_mov_b64_e32 v[36:37], v[4:5]
	v_mov_b64_e32 v[34:35], v[2:3]
	v_mov_b64_e32 v[32:33], v[0:1]
	v_mov_b64_e32 v[60:61], v[12:13]
	v_mov_b64_e32 v[58:59], v[10:11]
	v_mov_b64_e32 v[56:57], v[8:9]
	v_mov_b64_e32 v[54:55], v[6:7]
	v_mov_b64_e32 v[52:53], v[4:5]
	v_mov_b64_e32 v[50:51], v[2:3]
	v_mov_b64_e32 v[48:49], v[0:1]
	v_mov_b64_e32 v[76:77], v[12:13]
	v_mov_b64_e32 v[74:75], v[10:11]
	v_mov_b64_e32 v[72:73], v[8:9]
	v_mov_b64_e32 v[70:71], v[6:7]
	v_mov_b64_e32 v[68:69], v[4:5]
	v_mov_b64_e32 v[66:67], v[2:3]
	v_mov_b64_e32 v[64:65], v[0:1]
	v_mov_b32_e32 v195, 0
	v_mov_b64_e32 v[124:125], v[12:13]
	v_mov_b64_e32 v[122:123], v[10:11]
	v_mov_b64_e32 v[120:121], v[8:9]
	v_mov_b64_e32 v[118:119], v[6:7]
	v_mov_b64_e32 v[116:117], v[4:5]
	v_mov_b64_e32 v[114:115], v[2:3]
	v_mov_b64_e32 v[112:113], v[0:1]
	s_mov_b32 s0, 0
	s_mov_b32 s54, 0
	s_add_i32 s1, s54, 3
	s_cmp_lt_u32 s1, s44
	s_cselect_b32 s1, s1, s45
	s_lshl_b32 s8, s1, 6
	v_add_u32_e32 v2, s8, v174
	v_ashrrev_i32_e32 v3, 31, v2
	v_lshlrev_b64 v[2:3], 10, v[2:3]
	v_lshl_add_u64 v[6:7], s[8:9], 1, v[176:177]
	v_lshl_add_u64 v[2:3], v[182:183], 0, v[2:3]
	v_lshl_add_u64 v[4:5], v[6:7], 0, v[178:179]
	v_lshl_add_u64 v[6:7], v[6:7], 0, v[180:181]
	global_load_dwordx4 v[10:13], v[2:3], off
	s_nop 0
	global_load_dwordx4 v[2:5], v[4:5], off
	global_load_dwordx4 v[6:9], v[6:7], off
.LBB0_1072:
	s_add_i32 s57, s48, s54
	s_cmp_lt_i32 s57, 0
	s_cselect_b64 s[16:17], -1, 0
	s_add_i32 s56, s49, s47
	s_cmp_le_i32 s56, s46
	s_cselect_b64 s[4:5], -1, 0
	s_or_b64 s[18:19], s[16:17], s[4:5]
	s_mov_b32 s55, s51
	s_not_b64 s[4:5], s[18:19]
	s_andn2_b64 vcc, exec, s[18:19]
	s_mov_b32 s51, s0
	v_add_u32_e32 v248, s51, v190
	ds_read_b128 v[196:199], v248 offset:9216
	ds_read_b128 v[200:203], v248 offset:13824
	ds_read_b128 v[204:207], v248 offset:18432
	ds_read_b128 v[208:211], v248 offset:23040
	ds_read_b128 v[212:215], v248 offset:9248
	ds_read_b128 v[216:219], v248 offset:13856
	ds_read_b128 v[220:223], v248 offset:18464
	ds_read_b128 v[224:227], v248 offset:23072
	s_cbranch_vccnz .LBB0_1084
	s_cmp_lt_i32 s57, 0
	s_cbranch_scc0 .Ldiff_a_mask

.LBB0_1088:
	s_setprio 0
	s_add_i32 s0, s54, 4
	s_cmp_lt_u32 s54, s43
	s_cselect_b32 s0, s0, s45
	s_lshl_b32 s8, s0, 6
	v_add_u32_e32 v14, s8, v174
	v_ashrrev_i32_e32 v15, 31, v14
	v_lshlrev_b64 v[14:15], 10, v[14:15]
	v_lshl_add_u64 v[132:133], s[8:9], 1, v[176:177]
	v_lshl_add_u64 v[14:15], v[182:183], 0, v[14:15]
	v_lshl_add_u64 v[128:129], v[132:133], 0, v[178:179]
	global_load_dwordx4 v[136:139], v[14:15], off
	s_nop 0
	global_load_dwordx4 v[128:131], v[128:129], off
	v_lshl_add_u64 v[14:15], v[132:133], 0, v[180:181]
	global_load_dwordx4 v[132:135], v[14:15], off
	s_waitcnt lgkmcnt(0)
	s_barrier
	v_add_u32_e32 v248, s55, v190
	ds_read_b128 v[196:199], v248 offset:9216
	ds_read_b128 v[200:203], v248 offset:13824
	ds_read_b128 v[204:207], v248 offset:18432
	ds_read_b128 v[208:211], v248 offset:23040
	ds_read_b128 v[212:215], v248 offset:9248
	ds_read_b128 v[216:219], v248 offset:13856
	ds_read_b128 v[220:223], v248 offset:18464
	ds_read_b128 v[224:227], v248 offset:23072
	s_add_i32 s57, s57, 1
	s_cmp_lt_i32 s57, 0
	s_cselect_b64 s[0:1], -1, 0
	s_add_i32 s4, s56, 64
	s_cmp_le_i32 s4, s46
	s_cselect_b64 s[4:5], -1, 0
	s_or_b64 s[0:1], s[0:1], s[4:5]
	s_not_b64 s[4:5], s[0:1]
	s_andn2_b64 vcc, exec, s[0:1]
	s_cbranch_vccnz .LBB0_1094
	s_cmp_lt_i32 s57, 0
	s_cbranch_scc0 .Ldiff_b_mask

; template <int DK, int DV>
; __device__ __forceinline__ void attn_unit(LAS unsigned char* lds, const bf16* Qp, int ldq, const bf16* Kp, int ldk, const bf16* VTp, bf16* Op, int ldo, int qb) {
;     ...
;     for (int t = 0; t < NT; t += 2) {
;         ATT_STEP(t, kra, vra, krb, vrb);
;         ATT_STEP(t + 1, krb, vrb, kra, vra);
;     }
.LBB0_1098:
	s_setprio 0
	s_and_b64 vcc, exec, s[4:5]
	s_cbranch_vccnz .Ldiff_b_nold
	s_add_i32 s1, s54, 3
	s_cmp_lt_u32 s1, s44
	s_cselect_b32 s1, s1, s45
	s_lshl_b32 s8, s1, 6
	v_add_u32_e32 v2, s8, v174
	v_ashrrev_i32_e32 v3, 31, v2
	v_lshlrev_b64 v[2:3], 10, v[2:3]
	v_lshl_add_u64 v[6:7], s[8:9], 1, v[176:177]
	v_lshl_add_u64 v[2:3], v[182:183], 0, v[2:3]
	v_lshl_add_u64 v[4:5], v[6:7], 0, v[178:179]
	v_lshl_add_u64 v[6:7], v[6:7], 0, v[180:181]
	global_load_dwordx4 v[10:13], v[2:3], off
	s_nop 0
	global_load_dwordx4 v[2:5], v[4:5], off
	global_load_dwordx4 v[6:9], v[6:7], off
.Ldiff_b_nold:
	s_waitcnt lgkmcnt(0)
	s_barrier
	s_addk_i32 s47, 0x80
	s_and_b64 vcc, exec, s[4:5]
	s_cbranch_vccnz .LBB0_1100
	s_mov_b32 s0, s50
	s_mov_b32 s50, s55
	s_branch .LBB0_1072
